# P3 prologue restructure: bias-table/gain/k-sumsq loads all issued before the 16 row DMAs, consumed behind one vmcnt(16); plus earlier edits
# baseline (speedup 1.0000x reference)
; __global__ void __launch_bounds__(NWAVES * 64, 2) fwd(Args a) {
;     ...
;             __syncthreads();
;             { const int dr = tid >> 5, dc = tid & 31; tbl[tid] = (dr < 15 && dc < 31) ? a.in[I_RPB][h * 465 + dr * 31 + dc] * 1.4426950408889634f : -1e30f; }
;             if (tid < 64) qgt[tid] = a.in[I_QNG][tid] * a.in[I_KNG][tid];
;             bool sel[4]; int dsel[4]; unsigned psel[2];
;             { const int qc = 16 * j + l15, cs = min(max(qc - 8, 0), 48), o = cs - kc0;
; #pragma unroll
;               for (int e = 0; e < 4; ++e) { const int pp = 4 * fq + e; sel[e] = pp < o; dsel[e] = 4 * (kc0 + pp + (sel[e] ? 16 : 0) - qc + 15); }
;               psel[0] = (sel[0] ? 0u : 0xFFFFu) | (sel[1] ? 0u : 0xFFFF0000u); psel[1] = (sel[2] ? 0u : 0xFFFFu) | (sel[3] ? 0u : 0xFFFF0000u); }
;             const int koff0 = l15 * 128 + 16 * (fq ^ (l15 & 7)), koff1 = l15 * 128 + 16 * ((fq ^ (l15 & 7)) ^ 4);
;             int voff[4];
; #pragma unroll
;             for (int db = 0; db < 4; ++db) voff[db] = (4 * fq + tq) * 128 + 16 * ((2 * db + (tp >> 1)) ^ (4 * (fq & 1) + tq)) + 8 * (tp & 1);
;     ...
;             { const int lo0 = min(max(r0 - 4, 0), rows - 8);
;               for (int kr = lo0; kr < lo0 + 8; ++kr) STAGE_ROW(kr); }
.LBB0_234:
	v_mov_b32_e32 v249, 0xf149f2ca
	s_barrier
	s_and_saveexec_b64 s[98:99], s[0:1]
	s_cbranch_execz .Lqg_skip
	global_load_dword v240, v[130:131], off
	global_load_dword v241, v[128:129], off
.Lqg_skip:
	s_or_b64 exec, exec, s[98:99]
	s_and_saveexec_b64 s[12:13], s[48:49]
	s_cbranch_execz .LBB0_236
	s_mul_i32 s28, s52, 0x1d1
	v_add_u32_e32 v4, s28, v126
	v_readlane_b32 s68, v250, 20
	v_ashrrev_i32_e32 v5, 31, v4
	v_readlane_b32 s74, v250, 26
	v_readlane_b32 s75, v250, 27
	v_readlane_b32 s69, v250, 21
	v_readlane_b32 s70, v250, 22
	v_lshl_add_u64 v[4:5], v[4:5], 2, s[74:75]
	global_load_dword v249, v[4:5], off
	v_readlane_b32 s71, v250, 23
	v_readlane_b32 s72, v250, 24
	v_readlane_b32 s73, v250, 25
	v_readlane_b32 s76, v250, 28
	v_readlane_b32 s77, v250, 29
	v_readlane_b32 s78, v250, 30
	v_readlane_b32 s79, v250, 31
	v_readlane_b32 s80, v250, 32
	v_readlane_b32 s81, v250, 33
	v_readlane_b32 s82, v250, 34
	v_readlane_b32 s83, v250, 35
.LBB0_236:
	s_or_b64 exec, exec, s[12:13]
	s_and_saveexec_b64 s[12:13], s[0:1]
	s_cbranch_execz .LBB0_238
.LBB0_238:
	s_or_b64 exec, exec, s[12:13]
	s_lshl_b32 s12, s33, 4
	s_lshl_b32 s13, s22, 13
	s_and_b32 s42, s12, s23
	s_lshl_b32 s12, s22, 11
	s_add_i32 s13, s13, 0xffff4000
	s_cmp_lt_i32 s22, 8
	s_cselect_b32 s56, s12, s13
	v_sub_u32_e64 v2, s42, 4 clamp
	s_sub_i32 s12, s56, s61
	v_readfirstlane_b32 s13, v2
	s_lshl_b32 s70, s52, 6
	s_ashr_i32 s53, s52, 31
	s_min_u32 s22, s13, s84
	v_add_u32_e32 v193, s12, v171
	s_ashr_i32 s71, s70, 31
	s_lshl_b64 s[12:13], s[52:53], 17
	s_ashr_i32 s57, s56, 31
	s_add_u32 s23, s91, s12
	s_addc_u32 s28, s92, s13
	s_lshl_b64 s[12:13], s[56:57], 2
	s_add_u32 s12, s23, s12
	s_addc_u32 s13, s28, s13
	s_cmp_eq_u32 s88, 4
	s_cbranch_scc0 .Lrk_skip
	s_lshl_b32 s98, s22, 8
	s_add_u32 s98, s98, 0x100000
	s_add_u32 s98, s12, s98
	s_addc_u32 s99, s13, 0
	global_load_dword v240, v136, s[98:99]
	global_load_dword v241, v136, s[98:99] offset:256
	global_load_dword v242, v136, s[98:99] offset:512
	global_load_dword v243, v136, s[98:99] offset:768
	global_load_dword v244, v136, s[98:99] offset:1024
	global_load_dword v245, v136, s[98:99] offset:1280
	global_load_dword v246, v136, s[98:99] offset:1536
	global_load_dword v247, v136, s[98:99] offset:1792

; __global__ void __launch_bounds__(NWAVES * 64, 2) fwd(Args a) {
;     ...
;             { const int dr = tid >> 5, dc = tid & 31; tbl[tid] = (dr < 15 && dc < 31) ? a.in[I_RPB][h * 465 + dr * 31 + dc] * 1.4426950408889634f : -1e30f; }
;             if (tid < 64) qgt[tid] = a.in[I_QNG][tid] * a.in[I_KNG][tid];
;     ...
;             { const int lo0 = min(max(r0 - 4, 0), rows - 8);
;               for (int kr = lo0; kr < lo0 + 8; ++kr) STAGE_ROW(kr); }
;             const int pu0 = 128 * grp + 2 * task;
;             v4u qraw[2] = {{0u, 0u, 0u, 0u}, {0u, 0u, 0u, 0u}}; float qss = 0.f;
;             if (wave < 4) { const int qrow0 = base + r0 * 64 + 16 * j + l15; const bf16* qp0 = PROJg + (size_t)(qrow0 - GROWS * grp) * INW + h * 64 + 8 * fq;
;                 qss = hss[(size_t)h * MT + qrow0]; qraw[0] = *(const v4u*)qp0; qraw[1] = *(const v4u*)(qp0 + 32); }
.LBB0_254:
	s_waitcnt vmcnt(16)
	s_and_saveexec_b64 s[98:99], s[48:49]
	v_mul_f32_e32 v249, 0x3fb8aa3b, v249
	s_or_b64 exec, exec, s[98:99]
	ds_write_b32 v127, v249
	s_and_saveexec_b64 s[98:99], s[0:1]
	v_mul_f32_e32 v248, v240, v241
	ds_write_b32 v168, v248
	s_or_b64 exec, exec, s[98:99]
	s_andn2_b64 vcc, exec, s[46:47]
	s_mov_b64 s[72:73], -1
	s_cbranch_vccnz .LBB0_257
	s_lshl_b64 s[54:55], s[52:53], 17
	s_lshl_b32 s28, s42, 6
	v_mov_b32_e32 v74, 0
	s_cbranch_execz .LBB0_258
